# v3 + compress A-tile double buffer (one barrier per iteration) + scan inner loop re-emitted: hazard-free schedule, LDS operand reads issued half an iteration ahead
# speedup vs baseline: 1.0111x; 1.0085x over previous
; #define LAS __attribute__((address_space(3)))
; DI void unpack8(const v4u u, float (&f)[8]) { f[0] = bflo(u.x); f[1] = bfhi(u.x); f[2] = bflo(u.y); f[3] = bfhi(u.y); f[4] = bflo(u.z); f[5] = bfhi(u.z); f[6] = bflo(u.w); f[7] = bfhi(u.w); }
; DI v4u pack8(const float (&f)[8]) { v4u o; o.x = pk2(f[0], f[1]); o.y = pk2(f[2], f[3]); o.z = pk2(f[4], f[5]); o.w = pk2(f[6], f[7]); return o; }
; #define CMP_LOADB(dst, ll_) do { _Pragma("unroll") for (int ks = 0; ks < 2; ++ks) _Pragma("unroll") for (int ct = 0; ct < 2; ++ct) dst[ks][ct] = *(const bf16x8*)(W1T + (size_t)(32 * w + 16 * ct + fr) * 2048 + (ll_) * 64 + ks * 32 + fq * 8); } while (0)
; DI void nsa_compress_item(KA a, const int l, LAS unsigned char* lds, const int it) {
;     ...
;     for (int ll = 0; ll < 32; ++ll) {
;         __syncthreads();
;         if (stager) { float x1[8], x2[8], o1[8], o2[8]; unpack8(xr1, x1); unpack8(xr2, x2);
; #pragma unroll
;             for (int e = 0; e < 8; ++e) { float y1 = svalid ? x1[e] : 0.f, y2 = svalid ? x2[e] : 0.f;
;                 if (kv == 0 && svalid) { const float cc = cs[e >> 2][e & 3], ss = sn[e >> 2][e & 3]; y1 = x1[e] * cc - x2[e] * ss; y2 = x1[e] * ss + x2[e] * cc; }
;                 o1[e] = y1 + ps1[e >> 2][e & 3]; o2[e] = y2 + ps2[e >> 2][e & 3]; }
;             *(LAS v4u*)(At + sc_ * PA + 8 * sm_) = pack8(o1); *(LAS v4u*)(At + sc_ * PA + 32 + 8 * sm_) = pack8(o2); }
;         __syncthreads();
;         if (ll + 1 < 32) { CMP_LOADA(ll + 1); CMP_LOADB(bnxt, ll + 1); }
.LBB0_480:
	v_lshl_add_u64 v[132:133], s[56:57], 1, v[98:99]
	v_lshl_add_u64 v[134:135], v[132:133], 0, v[100:101]
	v_lshl_add_u64 v[132:133], v[132:133], 0, v[102:103]
	global_load_dwordx4 v[136:139], v[134:135], off
	global_load_dwordx4 v[140:143], v[132:133], off
	global_load_dwordx4 v[144:147], v[134:135], off offset:64
	global_load_dwordx4 v[148:151], v[132:133], off offset:64
	s_and_saveexec_b64 s[58:59], s[2:3]
	s_cbranch_execz .LBB0_482
	s_waitcnt vmcnt(8)
	v_lshlrev_b32_e32 v89, 16, v4
	v_lshlrev_b32_e32 v88, 16, v0
	v_mov_b32_e32 v90, v16
	v_mov_b32_e32 v91, v20
	v_pk_mul_f32 v[90:91], v[90:91], v[88:89]
	s_nop 0
	v_sub_f32_e32 v92, v90, v91
	v_mov_b32_e32 v90, v20
	v_mov_b32_e32 v91, v16
	v_pk_mul_f32 v[90:91], v[90:91], v[88:89]
	v_cndmask_b32_e64 v88, v88, v92, s[40:41]
	v_add_f32_e32 v90, v90, v91
	v_cndmask_b32_e64 v89, v89, v90, s[40:41]
	v_cndmask_b32_e64 v89, 0, v89, s[0:1]
	v_cndmask_b32_e64 v88, 0, v88, s[0:1]
	s_waitcnt vmcnt(6)
	v_add_f32_e32 v92, v36, v88
	s_waitcnt vmcnt(4)
	v_add_f32_e32 v93, v52, v89
	v_and_b32_e32 v89, 0xffff0000, v4
	v_and_b32_e32 v88, 0xffff0000, v0
	v_mov_b32_e32 v90, v17
	v_mov_b32_e32 v91, v21
	v_pk_mul_f32 v[90:91], v[90:91], v[88:89]
	s_nop 0
	v_sub_f32_e32 v94, v90, v91
	v_mov_b32_e32 v90, v21
	v_mov_b32_e32 v91, v17
	v_pk_mul_f32 v[90:91], v[90:91], v[88:89]
	v_cndmask_b32_e64 v88, v88, v94, s[40:41]
	v_add_f32_e32 v90, v90, v91
	v_cndmask_b32_e64 v89, v89, v90, s[40:41]
	v_cndmask_b32_e64 v89, 0, v89, s[0:1]
	v_cndmask_b32_e64 v88, 0, v88, s[0:1]
	v_add_f32_e32 v94, v37, v88
	v_add_f32_e32 v95, v53, v89
	v_lshlrev_b32_e32 v89, 16, v5
	v_lshlrev_b32_e32 v88, 16, v1
	v_mov_b32_e32 v90, v18
	v_mov_b32_e32 v91, v22
	v_pk_mul_f32 v[90:91], v[90:91], v[88:89]
	s_nop 0
	v_sub_f32_e32 v113, v90, v91
	v_mov_b32_e32 v90, v22
	v_mov_b32_e32 v91, v18
	v_pk_mul_f32 v[90:91], v[90:91], v[88:89]
	v_cndmask_b32_e64 v88, v88, v113, s[40:41]
	v_add_f32_e32 v90, v90, v91
	v_cndmask_b32_e64 v89, v89, v90, s[40:41]
	v_cndmask_b32_e64 v89, 0, v89, s[0:1]
	v_cndmask_b32_e64 v88, 0, v88, s[0:1]
	v_add_f32_e32 v113, v38, v88
	v_add_f32_e32 v115, v54, v89
	v_and_b32_e32 v89, 0xffff0000, v5
	v_and_b32_e32 v88, 0xffff0000, v1
	v_mov_b32_e32 v90, v19
	v_mov_b32_e32 v91, v23
	v_pk_mul_f32 v[90:91], v[90:91], v[88:89]
	s_nop 0
	v_sub_f32_e32 v122, v90, v91
	v_mov_b32_e32 v90, v23
	v_mov_b32_e32 v91, v19
	v_pk_mul_f32 v[90:91], v[90:91], v[88:89]
	v_cndmask_b32_e64 v88, v88, v122, s[40:41]
	v_add_f32_e32 v90, v90, v91
	v_cndmask_b32_e64 v89, v89, v90, s[40:41]
	v_cndmask_b32_e64 v89, 0, v89, s[0:1]
	v_cndmask_b32_e64 v88, 0, v88, s[0:1]
	v_add_f32_e32 v122, v39, v88
	v_add_f32_e32 v123, v55, v89
	v_lshlrev_b32_e32 v89, 16, v6
	v_lshlrev_b32_e32 v88, 16, v2
	v_mov_b32_e32 v90, v8
	v_mov_b32_e32 v91, v12
	v_pk_mul_f32 v[90:91], v[90:91], v[88:89]
	s_nop 0
	v_sub_f32_e32 v124, v90, v91
	v_mov_b32_e32 v90, v12
	v_mov_b32_e32 v91, v8
	v_pk_mul_f32 v[90:91], v[90:91], v[88:89]
	v_cndmask_b32_e64 v88, v88, v124, s[40:41]
	v_add_f32_e32 v90, v90, v91
	v_cndmask_b32_e64 v89, v89, v90, s[40:41]
	v_cndmask_b32_e64 v89, 0, v89, s[0:1]
	v_cndmask_b32_e64 v88, 0, v88, s[0:1]
	v_add_f32_e32 v124, v24, v88
	v_add_f32_e32 v125, v28, v89
	v_and_b32_e32 v89, 0xffff0000, v6
	v_and_b32_e32 v88, 0xffff0000, v2
	v_mov_b32_e32 v90, v9
	v_mov_b32_e32 v91, v13
	v_pk_mul_f32 v[90:91], v[90:91], v[88:89]
	s_nop 0
	v_sub_f32_e32 v126, v90, v91
	v_mov_b32_e32 v90, v13
	v_mov_b32_e32 v91, v9
	v_pk_mul_f32 v[90:91], v[90:91], v[88:89]
	v_cndmask_b32_e64 v88, v88, v126, s[40:41]
	v_add_f32_e32 v90, v90, v91
	v_cndmask_b32_e64 v89, v89, v90, s[40:41]
	v_cndmask_b32_e64 v89, 0, v89, s[0:1]
	v_cndmask_b32_e64 v88, 0, v88, s[0:1]
	v_add_f32_e32 v126, v25, v88
	v_add_f32_e32 v127, v29, v89
	v_lshlrev_b32_e32 v89, 16, v7
	v_lshlrev_b32_e32 v88, 16, v3
	v_mov_b32_e32 v90, v10
	v_mov_b32_e32 v91, v14
	v_pk_mul_f32 v[90:91], v[90:91], v[88:89]
	s_nop 0
	v_sub_f32_e32 v128, v90, v91
	v_mov_b32_e32 v90, v14
	v_mov_b32_e32 v91, v10
	v_pk_mul_f32 v[90:91], v[90:91], v[88:89]
	v_cndmask_b32_e64 v88, v88, v128, s[40:41]
	v_add_f32_e32 v90, v90, v91
	v_cndmask_b32_e64 v89, v89, v90, s[40:41]
	v_cndmask_b32_e64 v89, 0, v89, s[0:1]
	v_cndmask_b32_e64 v88, 0, v88, s[0:1]
	v_add_f32_e32 v128, v26, v88
	v_add_f32_e32 v129, v30, v89
	v_and_b32_e32 v89, 0xffff0000, v7
	v_and_b32_e32 v88, 0xffff0000, v3
	v_mov_b32_e32 v90, v11
	v_mov_b32_e32 v91, v15
	v_pk_mul_f32 v[90:91], v[90:91], v[88:89]
	s_nop 0
	v_sub_f32_e32 v130, v90, v91
	v_mov_b32_e32 v90, v15
	v_mov_b32_e32 v91, v11
	v_pk_mul_f32 v[90:91], v[90:91], v[88:89]
	v_cndmask_b32_e64 v88, v88, v130, s[40:41]
	v_add_f32_e32 v90, v90, v91
	v_cndmask_b32_e64 v89, v89, v90, s[40:41]
	v_cndmask_b32_e64 v88, 0, v88, s[0:1]
	v_cndmask_b32_e64 v89, 0, v89, s[0:1]
	v_add_f32_e32 v91, v27, v88
	v_add_f32_e32 v130, v31, v89
	v_cvt_pk_bf16_f32 v88, v92, v94
	v_cvt_pk_bf16_f32 v89, v113, v122
	v_cvt_pk_bf16_f32 v90, v124, v126
	v_cvt_pk_bf16_f32 v91, v128, v91
	ds_write_b128 v121, v[88:91]
	v_cvt_pk_bf16_f32 v88, v93, v95
	v_cvt_pk_bf16_f32 v89, v115, v123
	v_cvt_pk_bf16_f32 v90, v125, v127
	v_cvt_pk_bf16_f32 v91, v129, v130
	ds_write_b128 v121, v[88:91] offset:64

; #define LAS __attribute__((address_space(3)))
; DI f32x4 mma16(bf16x8 a, bf16x8 b, f32x4 c) { return __builtin_amdgcn_mfma_f32_16x16x32_bf16(a, b, c, 0, 0, 0); }
; #define CMP_LOADB(dst, ll_) do { _Pragma("unroll") for (int ks = 0; ks < 2; ++ks) _Pragma("unroll") for (int ct = 0; ct < 2; ++ct) dst[ks][ct] = *(const bf16x8*)(W1T + (size_t)(32 * w + 16 * ct + fr) * 2048 + (ll_) * 64 + ks * 32 + fq * 8); } while (0)
; DI void nsa_compress_item(KA a, const int l, LAS unsigned char* lds, const int it) {
;     ...
;         if (ll + 1 < 32) { CMP_LOADA(ll + 1); CMP_LOADB(bnxt, ll + 1); }
; #pragma unroll
;         for (int ks = 0; ks < 2; ++ks) {
; #pragma unroll
;             for (int rt = 0; rt < 4; ++rt) { const bf16x8 af = *(const LAS bf16x8*)(At + (16 * rt + fr) * PA + ks * 32 + fq * 8); acc[rt][0] = mma16(af, bcur[ks][0], acc[rt][0]); acc[rt][1] = mma16(af, bcur[ks][1], acc[rt][1]); } }
; #pragma unroll
;         for (int ks = 0; ks < 2; ++ks) { bcur[ks][0] = bnxt[ks][0]; bcur[ks][1] = bnxt[ks][1]; }
.Lcmp_wd:
	v_mov_b64_e32 v[80:81], v[136:137]
	v_mov_b64_e32 v[82:83], v[138:139]
	v_mov_b64_e32 v[84:85], v[140:141]
	v_mov_b64_e32 v[86:87], v[142:143]
	v_mov_b64_e32 v[76:77], v[144:145]
	v_mov_b64_e32 v[78:79], v[146:147]
	v_mov_b64_e32 v[68:69], v[148:149]
	v_mov_b64_e32 v[70:71], v[150:151]
	v_xor_b32_e32 v120, 0x4000, v120
	v_xor_b32_e32 v121, 0x4000, v121
	s_branch .LBB0_480
.Lcmp_exit:
	s_waitcnt vmcnt(0)
	v_mov_b64_e32 v[88:89], v[136:137]
	v_mov_b64_e32 v[90:91], v[138:139]
	v_mov_b64_e32 v[92:93], v[140:141]
	v_mov_b64_e32 v[94:95], v[142:143]
	v_mov_b64_e32 v[80:81], v[144:145]
	v_mov_b64_e32 v[82:83], v[146:147]
	v_mov_b64_e32 v[84:85], v[148:149]
	v_mov_b64_e32 v[86:87], v[150:151]
	v_xor_b32_e32 v120, 0x4000, v120
	v_xor_b32_e32 v121, 0x4000, v121

; #define LAS __attribute__((address_space(3)))
; DI void rwkv_scan2_item(KA a, LAS unsigned char* lds, const int item) {
;     ...
;             const LAS float* d_ = sb + (c & 1) * SBUF_F; LAS float* yo = yb + (c & 1) * SC * 32;
;             for (int t4 = 0; t4 < SC; t4 += 4) {
;                 f32x4 R4[4], W4[4], K4[4], A4[4], B4[4]; f32x2 V2[4]; float y0[4], y1[4];
; #pragma unroll
;                 for (int u = 0; u < 4; ++u) { const int o_ = (t4 + u) * 64 + 4 * kl;
;                     R4[u] = *(const LAS f32x4*)(d_ + o_); W4[u] = *(const LAS f32x4*)(d_ + SC * 64 + o_); K4[u] = *(const LAS f32x4*)(d_ + 2 * SC * 64 + o_);
;                     A4[u] = *(const LAS f32x4*)(d_ + 3 * SC * 64 + o_); B4[u] = *(const LAS f32x4*)(d_ + 4 * SC * 64 + o_); V2[u] = *(const LAS f32x2*)(d_ + 5 * SC * 64 + (t4 + u) * 32 + row0); }
.LBB0_591:
	s_and_saveexec_b64 s[36:37], s[0:1]
	s_cbranch_execz .LBB0_596
	v_cndmask_b32_e64 v37, 0, 1, s[30:31]
	s_mov_b32 s29, 0xb000
	v_mul_lo_u32 v38, v37, s29
	v_lshl_add_u32 v36, v37, 12, v5
	v_add_u32_e32 v37, v33, v38
	v_add_u32_e32 v38, v34, v38
	s_mov_b32 s29, -4
	ds_read2_b64 v[40:43], v37 offset1:16
	ds_read_b128 v[44:47], v38
	ds_read_b128 v[48:51], v38 offset:256
	ds_read_b128 v[52:55], v38 offset:8192
	ds_read_b128 v[56:59], v38 offset:8448
	ds_read_b128 v[60:63], v38 offset:16384
	ds_read_b128 v[64:67], v38 offset:16640
	ds_read_b128 v[68:71], v38 offset:24576
	ds_read_b128 v[72:75], v38 offset:24832
	ds_read_b128 v[76:79], v38 offset:32768
	ds_read_b128 v[80:83], v38 offset:33024
	s_branch .LBB0_594

; template <int CTRL> DI float ror_add(float x) { return x + __builtin_bit_cast(float, __builtin_amdgcn_update_dpp(0, __builtin_bit_cast(int, x), CTRL, 0xF, 0xF, true)); }
; DI void rwkv_scan2_item(KA a, LAS unsigned char* lds, const int item) {
;     ...
;                 for (int u = 0; u < 4; ++u) {
;                     const f32x2 a01 = {A4[u][0], A4[u][1]}, a23 = {A4[u][2], A4[u][3]}, b01 = {B4[u][0], B4[u][1]}, b23 = {B4[u][2], B4[u][3]};
;                     const f32x2 k01 = {K4[u][0], K4[u][1]}, k23 = {K4[u][2], K4[u][3]}, w01 = {W4[u][0], W4[u][1]}, w23 = {W4[u][2], W4[u][3]}, r01 = {R4[u][0], R4[u][1]}, r23 = {R4[u][2], R4[u][3]};
;                     f32x2 p0 = s00 * a01; p0 = s01 * a23 + p0; f32x2 p1 = s10 * a01; p1 = s11 * a23 + p1;
;                     float d0 = p0[0] + p0[1], d1 = p1[0] + p1[1];
;                     d0 = ror_add<0x128>(d0); d1 = ror_add<0x128>(d1); d0 = ror_add<0x124>(d0); d1 = ror_add<0x124>(d1); d0 = ror_add<0x122>(d0); d1 = ror_add<0x122>(d1); d0 = ror_add<0x121>(d0); d1 = ror_add<0x121>(d1);
;                     const float v0 = V2[u][0], v1 = V2[u][1];
;                     s00 = s00 * w01 + (k01 * v0 + b01 * d0); s01 = s01 * w23 + (k23 * v0 + b23 * d0);
;                     s10 = s10 * w01 + (k01 * v1 + b01 * d1); s11 = s11 * w23 + (k23 * v1 + b23 * d1);
;                     f32x2 q0 = s00 * r01; q0 = s01 * r23 + q0; f32x2 q1 = s10 * r01; q1 = s11 * r23 + q1;
;                     y0[u] = q0[0] + q0[1]; y1[u] = q1[0] + q1[1];
;                 }
.LBB0_594:
	ds_read2_b64 v[84:87], v37 offset0:32 offset1:48
	ds_read_b128 v[88:91], v38 offset:512
	ds_read_b128 v[92:95], v38 offset:768
	ds_read_b128 v[96:99], v38 offset:8704
	ds_read_b128 v[100:103], v38 offset:8960
	ds_read_b128 v[104:107], v38 offset:16896
	ds_read_b128 v[108:111], v38 offset:17152
	ds_read_b128 v[112:115], v38 offset:25088
	ds_read_b128 v[116:119], v38 offset:25344
	ds_read_b128 v[120:123], v38 offset:33280
	ds_read_b128 v[124:127], v38 offset:33536
	s_waitcnt lgkmcnt(11)
	v_pk_mul_f32 v[180:181], v[22:23], v[68:69]
	v_pk_mul_f32 v[182:183], v[26:27], v[68:69]
	v_pk_fma_f32 v[180:181], v[24:25], v[70:71], v[180:181]
	v_pk_fma_f32 v[182:183], v[28:29], v[70:71], v[182:183]
	v_add_f32_e32 v210, v180, v181
	v_add_f32_e32 v212, v182, v183
	v_pk_mul_f32 v[184:185], v[60:61], v[40:41] op_sel_hi:[1,0]
	v_add_f32_dpp v210, v210, v210 row_ror:8 row_mask:0xf bank_mask:0xf bound_ctrl:1
	v_add_f32_dpp v212, v212, v212 row_ror:8 row_mask:0xf bank_mask:0xf bound_ctrl:1
	v_pk_mul_f32 v[186:187], v[62:63], v[40:41] op_sel_hi:[1,0]
	v_add_f32_dpp v210, v210, v210 row_ror:4 row_mask:0xf bank_mask:0xf bound_ctrl:1
	v_add_f32_dpp v212, v212, v212 row_ror:4 row_mask:0xf bank_mask:0xf bound_ctrl:1
	v_pk_mul_f32 v[188:189], v[60:61], v[40:41] op_sel:[0,1]
	v_add_f32_dpp v210, v210, v210 row_ror:2 row_mask:0xf bank_mask:0xf bound_ctrl:1
	v_add_f32_dpp v212, v212, v212 row_ror:2 row_mask:0xf bank_mask:0xf bound_ctrl:1
	v_pk_mul_f32 v[190:191], v[62:63], v[40:41] op_sel:[0,1]
	v_add_f32_dpp v210, v210, v210 row_ror:1 row_mask:0xf bank_mask:0xf bound_ctrl:1
	v_add_f32_dpp v212, v212, v212 row_ror:1 row_mask:0xf bank_mask:0xf bound_ctrl:1
	v_pk_fma_f32 v[184:185], v[76:77], v[210:211], v[184:185] op_sel_hi:[1,0,1]
	v_pk_fma_f32 v[186:187], v[78:79], v[210:211], v[186:187] op_sel_hi:[1,0,1]
	v_pk_fma_f32 v[188:189], v[76:77], v[212:213], v[188:189] op_sel_hi:[1,0,1]
	v_pk_fma_f32 v[190:191], v[78:79], v[212:213], v[190:191] op_sel_hi:[1,0,1]
	v_pk_fma_f32 v[22:23], v[22:23], v[52:53], v[184:185]
	v_pk_fma_f32 v[24:25], v[24:25], v[54:55], v[186:187]
	v_pk_fma_f32 v[26:27], v[26:27], v[52:53], v[188:189]
	v_pk_fma_f32 v[28:29], v[28:29], v[54:55], v[190:191]
	v_pk_mul_f32 v[206:207], v[22:23], v[44:45]
	v_pk_mul_f32 v[208:209], v[26:27], v[44:45]
	v_pk_fma_f32 v[206:207], v[24:25], v[46:47], v[206:207]
	v_pk_fma_f32 v[208:209], v[28:29], v[46:47], v[208:209]
	v_add_f32_e32 v214, v206, v207
	v_add_f32_e32 v215, v208, v209
	v_pk_mul_f32 v[180:181], v[22:23], v[72:73]
	v_pk_mul_f32 v[182:183], v[26:27], v[72:73]
	v_pk_fma_f32 v[180:181], v[24:25], v[74:75], v[180:181]
	v_pk_fma_f32 v[182:183], v[28:29], v[74:75], v[182:183]
	v_add_f32_e32 v210, v180, v181
	v_add_f32_e32 v212, v182, v183
	v_pk_mul_f32 v[184:185], v[64:65], v[42:43] op_sel_hi:[1,0]
	v_add_f32_dpp v210, v210, v210 row_ror:8 row_mask:0xf bank_mask:0xf bound_ctrl:1
	v_add_f32_dpp v212, v212, v212 row_ror:8 row_mask:0xf bank_mask:0xf bound_ctrl:1
	v_pk_mul_f32 v[186:187], v[66:67], v[42:43] op_sel_hi:[1,0]
	v_add_f32_dpp v210, v210, v210 row_ror:4 row_mask:0xf bank_mask:0xf bound_ctrl:1
	v_add_f32_dpp v212, v212, v212 row_ror:4 row_mask:0xf bank_mask:0xf bound_ctrl:1
	v_pk_mul_f32 v[188:189], v[64:65], v[42:43] op_sel:[0,1]
	v_add_f32_dpp v210, v210, v210 row_ror:2 row_mask:0xf bank_mask:0xf bound_ctrl:1
	v_add_f32_dpp v212, v212, v212 row_ror:2 row_mask:0xf bank_mask:0xf bound_ctrl:1
	v_pk_mul_f32 v[190:191], v[66:67], v[42:43] op_sel:[0,1]
	v_add_f32_dpp v210, v210, v210 row_ror:1 row_mask:0xf bank_mask:0xf bound_ctrl:1
	v_add_f32_dpp v212, v212, v212 row_ror:1 row_mask:0xf bank_mask:0xf bound_ctrl:1
	v_pk_fma_f32 v[184:185], v[80:81], v[210:211], v[184:185] op_sel_hi:[1,0,1]
	v_pk_fma_f32 v[186:187], v[82:83], v[210:211], v[186:187] op_sel_hi:[1,0,1]
	v_pk_fma_f32 v[188:189], v[80:81], v[212:213], v[188:189] op_sel_hi:[1,0,1]
	v_pk_fma_f32 v[190:191], v[82:83], v[212:213], v[190:191] op_sel_hi:[1,0,1]
	v_pk_fma_f32 v[22:23], v[22:23], v[56:57], v[184:185]
	v_pk_fma_f32 v[24:25], v[24:25], v[58:59], v[186:187]
	v_pk_fma_f32 v[26:27], v[26:27], v[56:57], v[188:189]
	v_pk_fma_f32 v[28:29], v[28:29], v[58:59], v[190:191]
	v_pk_mul_f32 v[206:207], v[22:23], v[48:49]
	v_pk_mul_f32 v[208:209], v[26:27], v[48:49]
	v_pk_fma_f32 v[206:207], v[24:25], v[50:51], v[206:207]
	v_pk_fma_f32 v[208:209], v[28:29], v[50:51], v[208:209]
	v_add_f32_e32 v216, v206, v207
	v_add_f32_e32 v217, v208, v209
	ds_read2_b64 v[40:43], v37 offset0:64 offset1:80
	ds_read_b128 v[44:47], v38 offset:1024
	ds_read_b128 v[48:51], v38 offset:1280
	ds_read_b128 v[52:55], v38 offset:9216
	ds_read_b128 v[56:59], v38 offset:9472
	ds_read_b128 v[60:63], v38 offset:17408
	ds_read_b128 v[64:67], v38 offset:17664
	ds_read_b128 v[68:71], v38 offset:25600
	ds_read_b128 v[72:75], v38 offset:25856
	ds_read_b128 v[76:79], v38 offset:33792
	ds_read_b128 v[80:83], v38 offset:34048
	s_waitcnt lgkmcnt(11)
; DI void rwkv_scan2_item(KA a, LAS unsigned char* lds, const int item) {
;     ...
;                 for (int u = 0; u < 4; ++u) {
;                     const f32x2 a01 = {A4[u][0], A4[u][1]}, a23 = {A4[u][2], A4[u][3]}, b01 = {B4[u][0], B4[u][1]}, b23 = {B4[u][2], B4[u][3]};
;                     const f32x2 k01 = {K4[u][0], K4[u][1]}, k23 = {K4[u][2], K4[u][3]}, w01 = {W4[u][0], W4[u][1]}, w23 = {W4[u][2], W4[u][3]}, r01 = {R4[u][0], R4[u][1]}, r23 = {R4[u][2], R4[u][3]};
;                     f32x2 p0 = s00 * a01; p0 = s01 * a23 + p0; f32x2 p1 = s10 * a01; p1 = s11 * a23 + p1;
;                     float d0 = p0[0] + p0[1], d1 = p1[0] + p1[1];
;                     d0 = ror_add<0x128>(d0); d1 = ror_add<0x128>(d1); d0 = ror_add<0x124>(d0); d1 = ror_add<0x124>(d1); d0 = ror_add<0x122>(d0); d1 = ror_add<0x122>(d1); d0 = ror_add<0x121>(d0); d1 = ror_add<0x121>(d1);
;                     const float v0 = V2[u][0], v1 = V2[u][1];
;                     s00 = s00 * w01 + (k01 * v0 + b01 * d0); s01 = s01 * w23 + (k23 * v0 + b23 * d0);
;                     s10 = s10 * w01 + (k01 * v1 + b01 * d1); s11 = s11 * w23 + (k23 * v1 + b23 * d1);
;                     f32x2 q0 = s00 * r01; q0 = s01 * r23 + q0; f32x2 q1 = s10 * r01; q1 = s11 * r23 + q1;
;                     y0[u] = q0[0] + q0[1]; y1[u] = q1[0] + q1[1];
;                 }
;                 {
;                     const bool b3 = (kl & 8) != 0, b2 = (kl & 4) != 0, b1 = (kl & 2) != 0;
;                     float w4[4], x2[2];
; #pragma unroll
;                     for (int u = 0; u < 4; ++u) { const float keep = b3 ? y1[u] : y0[u], send = b3 ? y0[u] : y1[u]; w4[u] = keep + dppx<0x140>(send); }
; #pragma unroll
;                     for (int u = 0; u < 2; ++u) { const float keep = b2 ? w4[2 + u] : w4[u], send = b2 ? w4[u] : w4[2 + u]; x2[u] = keep + dppx<0x141>(send); }
;                     const float keep1 = b1 ? x2[1] : x2[0], send1 = b1 ? x2[0] : x2[1];
;                     float z = keep1 + dppx<0x1B>(send1);
;                     z = z + dppx<0xB1>(z);
;                     if ((kl & 1) == 0) yo[(row0 + (b3 ? 1 : 0)) * SC + t4 + (b2 ? 2 : 0) + (b1 ? 1 : 0)] = z;
;                 }
;             }
;         }
;         if (c + 1 < NCH) RW_STORE((c + 1) & 1);
	v_pk_mul_f32 v[180:181], v[22:23], v[112:113]
	v_pk_mul_f32 v[182:183], v[26:27], v[112:113]
	v_pk_fma_f32 v[180:181], v[24:25], v[114:115], v[180:181]
	v_pk_fma_f32 v[182:183], v[28:29], v[114:115], v[182:183]
	v_add_f32_e32 v210, v180, v181
	v_add_f32_e32 v212, v182, v183
	v_pk_mul_f32 v[184:185], v[104:105], v[84:85] op_sel_hi:[1,0]
	v_add_f32_dpp v210, v210, v210 row_ror:8 row_mask:0xf bank_mask:0xf bound_ctrl:1
	v_add_f32_dpp v212, v212, v212 row_ror:8 row_mask:0xf bank_mask:0xf bound_ctrl:1
	v_pk_mul_f32 v[186:187], v[106:107], v[84:85] op_sel_hi:[1,0]
	v_add_f32_dpp v210, v210, v210 row_ror:4 row_mask:0xf bank_mask:0xf bound_ctrl:1
	v_add_f32_dpp v212, v212, v212 row_ror:4 row_mask:0xf bank_mask:0xf bound_ctrl:1
	v_pk_mul_f32 v[188:189], v[104:105], v[84:85] op_sel:[0,1]
	v_add_f32_dpp v210, v210, v210 row_ror:2 row_mask:0xf bank_mask:0xf bound_ctrl:1
	v_add_f32_dpp v212, v212, v212 row_ror:2 row_mask:0xf bank_mask:0xf bound_ctrl:1
	v_pk_mul_f32 v[190:191], v[106:107], v[84:85] op_sel:[0,1]
	v_add_f32_dpp v210, v210, v210 row_ror:1 row_mask:0xf bank_mask:0xf bound_ctrl:1
	v_add_f32_dpp v212, v212, v212 row_ror:1 row_mask:0xf bank_mask:0xf bound_ctrl:1
	v_pk_fma_f32 v[184:185], v[120:121], v[210:211], v[184:185] op_sel_hi:[1,0,1]
	v_pk_fma_f32 v[186:187], v[122:123], v[210:211], v[186:187] op_sel_hi:[1,0,1]
	v_pk_fma_f32 v[188:189], v[120:121], v[212:213], v[188:189] op_sel_hi:[1,0,1]
	v_pk_fma_f32 v[190:191], v[122:123], v[212:213], v[190:191] op_sel_hi:[1,0,1]
	v_pk_fma_f32 v[22:23], v[22:23], v[96:97], v[184:185]
	v_pk_fma_f32 v[24:25], v[24:25], v[98:99], v[186:187]
	v_pk_fma_f32 v[26:27], v[26:27], v[96:97], v[188:189]
	v_pk_fma_f32 v[28:29], v[28:29], v[98:99], v[190:191]
	v_pk_mul_f32 v[206:207], v[22:23], v[88:89]
	v_pk_mul_f32 v[208:209], v[26:27], v[88:89]
	v_pk_fma_f32 v[206:207], v[24:25], v[90:91], v[206:207]
	v_pk_fma_f32 v[208:209], v[28:29], v[90:91], v[208:209]
	v_add_f32_e32 v218, v206, v207
	v_add_f32_e32 v219, v208, v209
	v_pk_mul_f32 v[180:181], v[22:23], v[116:117]
	v_pk_mul_f32 v[182:183], v[26:27], v[116:117]
	v_pk_fma_f32 v[180:181], v[24:25], v[118:119], v[180:181]
	v_pk_fma_f32 v[182:183], v[28:29], v[118:119], v[182:183]
	v_add_f32_e32 v210, v180, v181
	v_add_f32_e32 v212, v182, v183
	v_pk_mul_f32 v[184:185], v[108:109], v[86:87] op_sel_hi:[1,0]
	v_add_f32_dpp v210, v210, v210 row_ror:8 row_mask:0xf bank_mask:0xf bound_ctrl:1
	v_add_f32_dpp v212, v212, v212 row_ror:8 row_mask:0xf bank_mask:0xf bound_ctrl:1
	v_pk_mul_f32 v[186:187], v[110:111], v[86:87] op_sel_hi:[1,0]
	v_add_f32_dpp v210, v210, v210 row_ror:4 row_mask:0xf bank_mask:0xf bound_ctrl:1
	v_add_f32_dpp v212, v212, v212 row_ror:4 row_mask:0xf bank_mask:0xf bound_ctrl:1
	v_pk_mul_f32 v[188:189], v[108:109], v[86:87] op_sel:[0,1]
	v_add_f32_dpp v210, v210, v210 row_ror:2 row_mask:0xf bank_mask:0xf bound_ctrl:1
	v_add_f32_dpp v212, v212, v212 row_ror:2 row_mask:0xf bank_mask:0xf bound_ctrl:1
	v_pk_mul_f32 v[190:191], v[110:111], v[86:87] op_sel:[0,1]
	v_add_f32_dpp v210, v210, v210 row_ror:1 row_mask:0xf bank_mask:0xf bound_ctrl:1
	v_add_f32_dpp v212, v212, v212 row_ror:1 row_mask:0xf bank_mask:0xf bound_ctrl:1
	v_pk_fma_f32 v[184:185], v[124:125], v[210:211], v[184:185] op_sel_hi:[1,0,1]
	v_pk_fma_f32 v[186:187], v[126:127], v[210:211], v[186:187] op_sel_hi:[1,0,1]
	v_pk_fma_f32 v[188:189], v[124:125], v[212:213], v[188:189] op_sel_hi:[1,0,1]
	v_pk_fma_f32 v[190:191], v[126:127], v[212:213], v[190:191] op_sel_hi:[1,0,1]
	v_pk_fma_f32 v[22:23], v[22:23], v[100:101], v[184:185]
	v_pk_fma_f32 v[24:25], v[24:25], v[102:103], v[186:187]
	v_pk_fma_f32 v[26:27], v[26:27], v[100:101], v[188:189]
	v_pk_fma_f32 v[28:29], v[28:29], v[102:103], v[190:191]
	v_pk_mul_f32 v[220:221], v[22:23], v[92:93]
	v_pk_mul_f32 v[222:223], v[26:27], v[92:93]
	v_pk_fma_f32 v[220:221], v[24:25], v[94:95], v[220:221]
	v_pk_fma_f32 v[222:223], v[28:29], v[94:95], v[222:223]
	v_cndmask_b32_e64 v224, v218, v219, s[2:3]
	v_add_f32_e32 v220, v220, v221
	v_add_f32_e32 v221, v222, v223
	v_cndmask_b32_e64 v222, v215, v214, s[2:3]
	v_cndmask_b32_e64 v214, v214, v215, s[2:3]
	v_cndmask_b32_e64 v223, v216, v217, s[2:3]
	s_nop 0
	v_add_f32_dpp v214, v214, v222 row_mirror row_mask:0xf bank_mask:0xf bound_ctrl:1
	v_cndmask_b32_e64 v222, v217, v216, s[2:3]
	s_nop 1
	v_add_f32_dpp v222, v223, v222 row_mirror row_mask:0xf bank_mask:0xf bound_ctrl:1
	v_cndmask_b32_e64 v223, v219, v218, s[2:3]
	s_nop 1
	v_add_f32_dpp v223, v224, v223 row_mirror row_mask:0xf bank_mask:0xf bound_ctrl:1
	v_cndmask_b32_e64 v224, v221, v220, s[2:3]
	v_cndmask_b32_e64 v220, v220, v221, s[2:3]
	v_cndmask_b32_e64 v221, v223, v214, s[4:5]
	v_cndmask_b32_e64 v214, v214, v223, s[4:5]
	v_add_f32_dpp v220, v220, v224 row_mirror row_mask:0xf bank_mask:0xf bound_ctrl:1
	s_nop 0
	v_add_f32_dpp v214, v214, v221 row_half_mirror row_mask:0xf bank_mask:0xf bound_ctrl:1
	v_cndmask_b32_e64 v221, v220, v222, s[4:5]
	v_cndmask_b32_e64 v220, v222, v220, s[4:5]
	s_nop 1
	v_add_f32_dpp v220, v220, v221 row_half_mirror row_mask:0xf bank_mask:0xf bound_ctrl:1
	v_cndmask_b32_e64 v221, v220, v214, s[6:7]
	v_cndmask_b32_e64 v214, v214, v220, s[6:7]
	s_nop 1
	v_add_f32_dpp v214, v214, v221 quad_perm:[3,2,1,0] row_mask:0xf bank_mask:0xf bound_ctrl:1
	s_nop 1
	v_mov_b32_dpp v220, v214 quad_perm:[1,0,3,2] row_mask:0xf bank_mask:0xf bound_ctrl:1
	s_and_saveexec_b64 s[38:39], s[8:9]
	s_cbranch_execz .LBB0_593
	v_add_f32_e32 v214, v214, v220
	ds_write_b32 v36, v214
	s_branch .LBB0_593
.LBB0_596:
	s_waitcnt lgkmcnt(0)
	s_or_b64 exec, exec, s[36:37]
	s_andn2_b64 vcc, exec, s[34:35]
	s_cbranch_vccnz .LBB0_586
	s_bitcmp1_b32 s27, 0
	s_cselect_b32 s29, 0xb000, 0
	s_add_i32 s29, s29, 0
	s_waitcnt vmcnt(4)
	v_lshlrev_b32_e32 v36, 16, v8
	v_and_b32_e32 v37, 0xffff0000, v8
	v_lshlrev_b32_e32 v38, 16, v9
	v_and_b32_e32 v39, 0xffff0000, v9
	v_lshl_add_u32 v40, v7, 2, s29
	ds_write_b128 v40, v[36:39]
	ds_write_b128 v40, v[0:3] offset:8192
	s_waitcnt vmcnt(3)
	v_lshlrev_b32_e32 v36, 16, v10
	v_and_b32_e32 v37, 0xffff0000, v10
	v_lshlrev_b32_e32 v38, 16, v11
	v_and_b32_e32 v39, 0xffff0000, v11
	ds_write_b128 v40, v[36:39] offset:16384
	s_waitcnt vmcnt(2)
	v_lshlrev_b32_e32 v36, 16, v12
	v_and_b32_e32 v37, 0xffff0000, v12
	v_lshlrev_b32_e32 v38, 16, v13
	v_and_b32_e32 v39, 0xffff0000, v13
	ds_write_b128 v40, v[36:39] offset:24576
	s_waitcnt vmcnt(1)
	v_lshlrev_b32_e32 v36, 16, v14
	v_and_b32_e32 v37, 0xffff0000, v14
	v_lshlrev_b32_e32 v38, 16, v15
	v_and_b32_e32 v39, 0xffff0000, v15
	ds_write_b128 v40, v[36:39] offset:32768
	v_lshlrev_b32_e32 v38, 2, v6
	s_waitcnt vmcnt(0)
	v_lshlrev_b32_e32 v36, 16, v30
	v_and_b32_e32 v37, 0xffff0000, v30
	v_add3_u32 v38, s29, v35, v38
	ds_write_b64 v38, v[36:37] offset:40960
	s_branch .LBB0_586
